# dx and post_diag (gla/hgrn) phases as hand-written row loops; first grid sync through the xcd barrier
# speedup vs baseline: 1.0432x; 1.0127x over previous
; DI f32x4 bf4_to_f4(u32x2 w) { return (f32x4){__uint_as_float(w.x << 16), __uint_as_float(w.x & 0xffff0000u), __uint_as_float(w.y << 16), __uint_as_float(w.y & 0xffff0000u)}; }
; template <int KIND> DI void post_diag_phase(const PZ& p, int wave, int lane) {
;     const int gw = blockIdx.x * 8 + wave, NGW = gridDim.x * 8;
;     const bf16_t* big = (const bf16_t*)(p.ws() + WS_BIG);
;     const bf16_t* OG = (const bf16_t*)(p.ws() + WS_Y);
;     bf16_t* HA = (bf16_t*)(p.ws() + WS_HA);
;     const float* gn = KIND == 0 ? p.in(19) : p.in(40);
;     for (int m = gw; m < MTOK; m += NGW) {
;         if (KIND == 1 && (m % TT) < NCTX) continue;
;         const bf16_t* of = big + (size_t)m * 4096 + (KIND == 0 ? 2048 : 1024);
; #pragma unroll
;         for (int j = 0; j < 4; ++j) {
;             const f32x4 o = bf4_to_f4(__builtin_nontemporal_load((const u32x2*)of + lane + 64 * j)) + bf4_to_f4(__builtin_nontemporal_load((const u32x2*)(of + 1024) + lane + 64 * j));
;             float ss = o.x * o.x + o.y * o.y + o.z * o.z + o.w * o.w;
; __global__ void __launch_bounds__(512, 2) mega_fwd(P kp) {
;     ...
;         const int kind = kPhaseKind[ph], layer = kPhaseLayer[ph];
;     ...
;         switch (kind) {
.LBB0_8:
	v_writelane_b32 v255, s6, 27
	v_writelane_b32 v255, s4, 28
	s_mov_b32 s86, s31
	v_readlane_b32 s4, v254, 42
	s_ashr_i32 s87, s86, 31
	v_readlane_b32 s6, v254, 44
	v_readlane_b32 s7, v254, 45
	s_add_u32 s58, s6, s86
	s_addc_u32 s59, s7, s87
	s_add_u32 s10, s58, 0x9100000
	s_addc_u32 s11, s59, 0
	s_add_u32 s38, s58, 0x12100000
	v_mov_b32_e32 v168, v155
	s_addc_u32 s39, s59, 0
	s_add_u32 s26, s58, 0x1b100000
	v_readfirstlane_b32 s2, v168
	s_addc_u32 s27, s59, 0
	s_ashr_i32 s4, s16, 31
	v_writelane_b32 v255, s2, 29
	s_ashr_i32 s2, s2, 6
	v_writelane_b32 v255, s2, 30
	s_getpc_b64 s[2:3]
	s_add_u32 s2, s2, kPhaseKind@rel32@lo+4
	s_addc_u32 s3, s3, kPhaseKind@rel32@hi+12
	s_add_u32 s2, s2, s16
	s_addc_u32 s3, s3, s4
	global_load_ubyte v0, v3, s[2:3]
	v_mov_b32_e32 v1, 11
	v_writelane_b32 v255, s16, 31
	s_mov_b32 s12, 0x358637bd
	s_mov_b32 s93, 0x12100000
	v_writelane_b32 v255, s4, 32
	v_and_b32_e32 v166, 63, v168
	s_mov_b64 s[16:17], -1
	v_readlane_b32 s5, v254, 43
	s_waitcnt vmcnt(0)
	v_cmp_lt_i32_sdwa s[2:3], v0, v1 src0_sel:WORD_0 src1_sel:DWORD
	v_readfirstlane_b32 s73, v0
	s_and_b64 vcc, exec, s[2:3]
	s_cbranch_vccnz .LBB0_1135
	s_and_b32 s2, 0xffff, s73
	s_cmp_lt_i32 s2, 22
	s_cbranch_scc1 .LBB0_103
	s_cmp_lt_i32 s2, 30
	s_cbranch_scc1 .LBB0_32
	s_cmp_lt_i32 s2, 31
	s_cbranch_scc1 .LBB0_26
	s_cmp_lt_i32 s2, 32
	s_cbranch_scc1 .LBB0_21
	s_cmp_eq_u32 s2, 32
	s_cbranch_scc0 .LBB0_20
	v_readlane_b32 s3, v252, 6
	v_readlane_b32 s4, v255, 30
	s_add_i32 s16, s4, s3
	s_cmp_gt_i32 s16, 0x11fff
	s_cbranch_scc1 .LBB0_20
	s_load_dwordx2 s[44:45], s[90:91], 0x158
	s_load_dwordx2 s[46:47], s[90:91], 0x140
	v_lshlrev_b32_e32 v1, 3, v166
	v_and_b32_e32 v0, 31, v166
	v_lshlrev_b32_e32 v0, 4, v0
	s_mov_b32 s54, 0
	s_mov_b32 s55, -1
	v_mov_b32_e32 v2, 0x3c000000
	s_waitcnt lgkmcnt(0)
	global_load_dwordx4 v[4:7], v0, s[46:47]
	s_add_u32 s40, s44, 0x1b100000
	s_addc_u32 s41, s45, 0
	s_add_u32 s40, s40, 0x800
	s_addc_u32 s41, s41, 0
	s_add_u32 s42, s44, 0x12100000
	s_addc_u32 s43, s45, 0
	s_add_u32 s48, s44, 0x9100000
	s_addc_u32 s49, s45, 0
.Lpd1_row:
	s_mul_hi_i32 s21, s16, 0x38e38e39
	s_lshr_b32 s23, s21, 31
	s_ashr_i32 s21, s21, 9
	s_add_i32 s21, s21, s23
	s_mul_i32 s23, s21, 0xfffff700
	s_add_i32 s23, s23, s16
	s_cmpk_lt_i32 s23, 0x100
	s_cbranch_scc1 .Lpd1_next
	s_lshl_b32 s25, s16, 13
	s_add_u32 s4, s40, s25
	s_addc_u32 s5, s41, 0
	s_lshl_b32 s25, s16, 11
	s_add_u32 s6, s42, s25
	s_addc_u32 s7, s43, 0
	s_add_u32 s52, s48, s25
	s_addc_u32 s53, s49, 0
	global_load_dwordx2 v[8:9], v1, s[4:5] offset:0 nt
	global_load_dwordx2 v[10:11], v1, s[4:5] offset:512 nt
	global_load_dwordx2 v[12:13], v1, s[4:5] offset:1024 nt
	global_load_dwordx2 v[14:15], v1, s[4:5] offset:1536 nt
	global_load_dwordx2 v[16:17], v1, s[4:5] offset:2048 nt
	global_load_dwordx2 v[18:19], v1, s[4:5] offset:2560 nt
	global_load_dwordx2 v[20:21], v1, s[4:5] offset:3072 nt
	global_load_dwordx2 v[22:23], v1, s[4:5] offset:3584 nt
	global_load_dwordx2 v[24:25], v1, s[6:7] offset:0 nt
	global_load_dwordx2 v[26:27], v1, s[6:7] offset:512 nt
	global_load_dwordx2 v[28:29], v1, s[6:7] offset:1024 nt
	global_load_dwordx2 v[30:31], v1, s[6:7] offset:1536 nt
	s_waitcnt vmcnt(4)
	v_lshlrev_b32_e32 v32, 16, v8
	v_and_b32_e32 v33, 0xffff0000, v8
	v_lshlrev_b32_e32 v34, 16, v9
	v_and_b32_e32 v35, 0xffff0000, v9
	v_lshlrev_b32_e32 v52, 16, v16
	v_and_b32_e32 v53, 0xffff0000, v16
	v_lshlrev_b32_e32 v54, 16, v17
	v_and_b32_e32 v55, 0xffff0000, v17
	v_add_f32_e32 v32, v32, v52
	v_add_f32_e32 v33, v33, v53
	v_add_f32_e32 v34, v34, v54
	v_add_f32_e32 v35, v35, v55
	v_lshlrev_b32_e32 v36, 16, v10
	v_and_b32_e32 v37, 0xffff0000, v10
	v_lshlrev_b32_e32 v38, 16, v11
	v_and_b32_e32 v39, 0xffff0000, v11
	v_lshlrev_b32_e32 v56, 16, v18
	v_and_b32_e32 v57, 0xffff0000, v18
	v_lshlrev_b32_e32 v58, 16, v19
	v_and_b32_e32 v59, 0xffff0000, v19
	v_add_f32_e32 v36, v36, v56
	v_add_f32_e32 v37, v37, v57
	v_add_f32_e32 v38, v38, v58
	v_add_f32_e32 v39, v39, v59
	v_lshlrev_b32_e32 v40, 16, v12
	v_and_b32_e32 v41, 0xffff0000, v12
	v_lshlrev_b32_e32 v42, 16, v13
	v_and_b32_e32 v43, 0xffff0000, v13
	v_lshlrev_b32_e32 v60, 16, v20
	v_and_b32_e32 v61, 0xffff0000, v20
	v_lshlrev_b32_e32 v62, 16, v21
	v_and_b32_e32 v63, 0xffff0000, v21
	v_add_f32_e32 v40, v40, v60
	v_add_f32_e32 v41, v41, v61
	v_add_f32_e32 v42, v42, v62
	v_add_f32_e32 v43, v43, v63
	v_lshlrev_b32_e32 v44, 16, v14
	v_and_b32_e32 v45, 0xffff0000, v14
	v_lshlrev_b32_e32 v46, 16, v15
	v_and_b32_e32 v47, 0xffff0000, v15
	v_lshlrev_b32_e32 v64, 16, v22
	v_and_b32_e32 v65, 0xffff0000, v22
	v_lshlrev_b32_e32 v66, 16, v23
	v_and_b32_e32 v67, 0xffff0000, v23
	v_add_f32_e32 v44, v44, v64
	v_add_f32_e32 v45, v45, v65
	v_add_f32_e32 v46, v46, v66
	v_add_f32_e32 v47, v47, v67
	v_mul_f32_e32 v48, v32, v32
	v_mul_f32_e32 v49, v36, v36
	v_mul_f32_e32 v50, v40, v40
	v_mul_f32_e32 v51, v44, v44
	v_fmac_f32_e32 v48, v33, v33
	v_fmac_f32_e32 v49, v37, v37
	v_fmac_f32_e32 v50, v41, v41
	v_fmac_f32_e32 v51, v45, v45
	v_fmac_f32_e32 v48, v34, v34
	v_fmac_f32_e32 v49, v38, v38
	v_fmac_f32_e32 v50, v42, v42
	v_fmac_f32_e32 v51, v46, v46
	v_fmac_f32_e32 v48, v35, v35
	v_fmac_f32_e32 v49, v39, v39
	v_fmac_f32_e32 v50, v43, v43
	v_fmac_f32_e32 v51, v47, v47
; DI float red16(float v) { v += DPPF(v, 0xB1); v += DPPF(v, 0x4E); v += DPPF(v, 0x141); v += DPPF(v, 0x140); return v; }
; DI f32x4 bf4_to_f4(u32x2 w) { return (f32x4){__uint_as_float(w.x << 16), __uint_as_float(w.x & 0xffff0000u), __uint_as_float(w.y << 16), __uint_as_float(w.y & 0xffff0000u)}; }
; DI u32x2 f4_to_bf4(f32x4 v) { return (u32x2){pk2(v.x, v.y), pk2(v.z, v.w)}; }
; template <int KIND> DI void post_diag_phase(const PZ& p, int wave, int lane) {
;     ...
;             const f32x4 o = bf4_to_f4(__builtin_nontemporal_load((const u32x2*)of + lane + 64 * j)) + bf4_to_f4(__builtin_nontemporal_load((const u32x2*)(of + 1024) + lane + 64 * j));
;             float ss = o.x * o.x + o.y * o.y + o.z * o.z + o.w * o.w;
;             float rstd; f32x4 g4;
;             if (KIND == 0) { rstd = rsqrtf(wave_sum(ss) * (1.f / 256.f) + 1e-6f); g4 = *((const f32x4*)gn + lane); }
;             else { ss = red16(ss); ss += __shfl_xor(ss, 16); rstd = rsqrtf(ss * (1.f / 128.f) + 1e-6f); g4 = *((const f32x4*)gn + (lane & 31)); }
;             const f32x4 og = bf4_to_f4(__builtin_nontemporal_load((const u32x2*)(OG + (size_t)m * 1024) + lane + 64 * j));
;             *((u32x2*)(HA + (size_t)m * 1024) + lane + 64 * j) = f4_to_bf4(o * rstd * g4 * og);
	v_add_f32_dpp v48, v48, v48 quad_perm:[1,0,3,2] row_mask:0xf bank_mask:0xf bound_ctrl:1
	v_add_f32_dpp v49, v49, v49 quad_perm:[1,0,3,2] row_mask:0xf bank_mask:0xf bound_ctrl:1
	v_add_f32_dpp v50, v50, v50 quad_perm:[1,0,3,2] row_mask:0xf bank_mask:0xf bound_ctrl:1
	v_add_f32_dpp v51, v51, v51 quad_perm:[1,0,3,2] row_mask:0xf bank_mask:0xf bound_ctrl:1
	v_add_f32_dpp v48, v48, v48 quad_perm:[2,3,0,1] row_mask:0xf bank_mask:0xf bound_ctrl:1
	v_add_f32_dpp v49, v49, v49 quad_perm:[2,3,0,1] row_mask:0xf bank_mask:0xf bound_ctrl:1
	v_add_f32_dpp v50, v50, v50 quad_perm:[2,3,0,1] row_mask:0xf bank_mask:0xf bound_ctrl:1
	v_add_f32_dpp v51, v51, v51 quad_perm:[2,3,0,1] row_mask:0xf bank_mask:0xf bound_ctrl:1
	v_add_f32_dpp v48, v48, v48 row_half_mirror row_mask:0xf bank_mask:0xf bound_ctrl:1
	v_add_f32_dpp v49, v49, v49 row_half_mirror row_mask:0xf bank_mask:0xf bound_ctrl:1
	v_add_f32_dpp v50, v50, v50 row_half_mirror row_mask:0xf bank_mask:0xf bound_ctrl:1
	v_add_f32_dpp v51, v51, v51 row_half_mirror row_mask:0xf bank_mask:0xf bound_ctrl:1
	v_add_f32_dpp v48, v48, v48 row_mirror row_mask:0xf bank_mask:0xf bound_ctrl:1
	v_add_f32_dpp v49, v49, v49 row_mirror row_mask:0xf bank_mask:0xf bound_ctrl:1
	v_add_f32_dpp v50, v50, v50 row_mirror row_mask:0xf bank_mask:0xf bound_ctrl:1
	v_add_f32_dpp v51, v51, v51 row_mirror row_mask:0xf bank_mask:0xf bound_ctrl:1
	s_nop 0
	v_readlane_b32 s3, v48, 0
	v_readlane_b32 s8, v48, 16
	v_readlane_b32 s12, v48, 32
	v_readlane_b32 s21, v48, 48
	v_readlane_b32 s23, v49, 0
	v_readlane_b32 s25, v49, 16
	v_readlane_b32 s30, v49, 32
	v_readlane_b32 s32, v49, 48
	s_nop 1
	v_mov_b32_e32 v48, s3
	v_mov_b32_e32 v72, s12
	v_mov_b32_e32 v49, s23
	v_mov_b32_e32 v73, s30
	v_add_f32_e32 v48, s8, v48
	v_add_f32_e32 v74, s21, v72
	v_add_f32_e32 v49, s25, v49
	v_add_f32_e32 v75, s32, v73
	v_cndmask_b32_e64 v48, v48, v74, s[54:55]
	v_cndmask_b32_e64 v49, v49, v75, s[54:55]
	s_nop 0
	v_readlane_b32 s3, v50, 0
	v_readlane_b32 s8, v50, 16
	v_readlane_b32 s12, v50, 32
	v_readlane_b32 s21, v50, 48
	v_readlane_b32 s23, v51, 0
	v_readlane_b32 s25, v51, 16
	v_readlane_b32 s30, v51, 32
	v_readlane_b32 s32, v51, 48
	s_nop 1
	v_mov_b32_e32 v50, s3
	v_mov_b32_e32 v72, s12
	v_mov_b32_e32 v51, s23
	v_mov_b32_e32 v73, s30
	v_add_f32_e32 v50, s8, v50
	v_add_f32_e32 v74, s21, v72
	v_add_f32_e32 v51, s25, v51
	v_add_f32_e32 v75, s32, v73
	v_cndmask_b32_e64 v50, v50, v74, s[54:55]
	v_cndmask_b32_e64 v51, v51, v75, s[54:55]
	v_fmaak_f32 v48, v2, v48, 0x358637bd
	v_fmaak_f32 v49, v2, v49, 0x358637bd
	v_fmaak_f32 v50, v2, v50, 0x358637bd
	v_fmaak_f32 v51, v2, v51, 0x358637bd
	v_rsq_f32_e32 v48, v48
	v_rsq_f32_e32 v49, v49
	v_rsq_f32_e32 v50, v50
	v_rsq_f32_e32 v51, v51
	s_waitcnt vmcnt(0)
	v_lshlrev_b32_e32 v52, 16, v24
	v_and_b32_e32 v53, 0xffff0000, v24
	v_lshlrev_b32_e32 v54, 16, v25
	v_and_b32_e32 v55, 0xffff0000, v25
	v_lshlrev_b32_e32 v56, 16, v26
	v_and_b32_e32 v57, 0xffff0000, v26
	v_lshlrev_b32_e32 v58, 16, v27
	v_and_b32_e32 v59, 0xffff0000, v27
	v_lshlrev_b32_e32 v60, 16, v28
	v_and_b32_e32 v61, 0xffff0000, v28
	v_lshlrev_b32_e32 v62, 16, v29
	v_and_b32_e32 v63, 0xffff0000, v29
	v_lshlrev_b32_e32 v64, 16, v30
	v_and_b32_e32 v65, 0xffff0000, v30
	v_lshlrev_b32_e32 v66, 16, v31
	v_and_b32_e32 v67, 0xffff0000, v31
	v_mul_f32_e32 v32, v32, v48
	v_mul_f32_e32 v36, v36, v49
	v_mul_f32_e32 v40, v40, v50
	v_mul_f32_e32 v44, v44, v51
	v_mul_f32_e32 v33, v33, v48
	v_mul_f32_e32 v37, v37, v49
	v_mul_f32_e32 v41, v41, v50
	v_mul_f32_e32 v45, v45, v51
	v_mul_f32_e32 v34, v34, v48
	v_mul_f32_e32 v38, v38, v49
	v_mul_f32_e32 v42, v42, v50
	v_mul_f32_e32 v46, v46, v51
	v_mul_f32_e32 v35, v35, v48
	v_mul_f32_e32 v39, v39, v49
	v_mul_f32_e32 v43, v43, v50
	v_mul_f32_e32 v47, v47, v51
	v_mul_f32_e32 v32, v32, v4
	v_mul_f32_e32 v36, v36, v4
	v_mul_f32_e32 v40, v40, v4
	v_mul_f32_e32 v44, v44, v4
	v_mul_f32_e32 v33, v33, v5
	v_mul_f32_e32 v37, v37, v5
	v_mul_f32_e32 v41, v41, v5
	v_mul_f32_e32 v45, v45, v5
	v_mul_f32_e32 v34, v34, v6
	v_mul_f32_e32 v38, v38, v6
	v_mul_f32_e32 v42, v42, v6
	v_mul_f32_e32 v46, v46, v6
	v_mul_f32_e32 v35, v35, v7
	v_mul_f32_e32 v39, v39, v7
	v_mul_f32_e32 v43, v43, v7
	v_mul_f32_e32 v47, v47, v7
	v_mul_f32_e32 v32, v32, v52
	v_mul_f32_e32 v36, v36, v56
	v_mul_f32_e32 v40, v40, v60
	v_mul_f32_e32 v44, v44, v64
	v_mul_f32_e32 v33, v33, v53
	v_mul_f32_e32 v37, v37, v57
	v_mul_f32_e32 v41, v41, v61
	v_mul_f32_e32 v45, v45, v65
	v_mul_f32_e32 v34, v34, v54
	v_mul_f32_e32 v38, v38, v58
	v_mul_f32_e32 v42, v42, v62
	v_mul_f32_e32 v46, v46, v66
	v_mul_f32_e32 v35, v35, v55
	v_mul_f32_e32 v39, v39, v59
	v_mul_f32_e32 v43, v43, v63
	v_mul_f32_e32 v47, v47, v67
	v_cvt_pk_bf16_f32 v8, v32, v33
	v_cvt_pk_bf16_f32 v9, v34, v35
	v_cvt_pk_bf16_f32 v10, v36, v37
	v_cvt_pk_bf16_f32 v11, v38, v39
	v_cvt_pk_bf16_f32 v12, v40, v41
	v_cvt_pk_bf16_f32 v13, v42, v43
	v_cvt_pk_bf16_f32 v14, v44, v45
	v_cvt_pk_bf16_f32 v15, v46, v47
	global_store_dwordx2 v1, v[8:9], s[52:53] offset:0
	global_store_dwordx2 v1, v[10:11], s[52:53] offset:512
	global_store_dwordx2 v1, v[12:13], s[52:53] offset:1024
	global_store_dwordx2 v1, v[14:15], s[52:53] offset:1536
.Lpd1_next:
	s_add_i32 s16, s16, s92
	s_cmp_gt_i32 s16, 0x11fff
	s_cbranch_scc0 .Lpd1_row

; DI float red16(float v) { v += DPPF(v, 0xB1); v += DPPF(v, 0x4E); v += DPPF(v, 0x141); v += DPPF(v, 0x140); return v; }
; DI f32x4 bf4_to_f4(u32x2 w) { return (f32x4){__uint_as_float(w.x << 16), __uint_as_float(w.x & 0xffff0000u), __uint_as_float(w.y << 16), __uint_as_float(w.y & 0xffff0000u)}; }
; template <int KIND> DI void post_diag_phase(const PZ& p, int wave, int lane) {
;     const int gw = blockIdx.x * 8 + wave, NGW = gridDim.x * 8;
;     const bf16_t* big = (const bf16_t*)(p.ws() + WS_BIG);
;     const bf16_t* OG = (const bf16_t*)(p.ws() + WS_Y);
;     bf16_t* HA = (bf16_t*)(p.ws() + WS_HA);
;     const float* gn = KIND == 0 ? p.in(19) : p.in(40);
;     for (int m = gw; m < MTOK; m += NGW) {
;         if (KIND == 1 && (m % TT) < NCTX) continue;
;         const bf16_t* of = big + (size_t)m * 4096 + (KIND == 0 ? 2048 : 1024);
; #pragma unroll
;         for (int j = 0; j < 4; ++j) {
;             const f32x4 o = bf4_to_f4(__builtin_nontemporal_load((const u32x2*)of + lane + 64 * j)) + bf4_to_f4(__builtin_nontemporal_load((const u32x2*)(of + 1024) + lane + 64 * j));
;             float ss = o.x * o.x + o.y * o.y + o.z * o.z + o.w * o.w;
;             float rstd; f32x4 g4;
;             if (KIND == 0) { rstd = rsqrtf(wave_sum(ss) * (1.f / 256.f) + 1e-6f); g4 = *((const f32x4*)gn + lane); }
;             else { ss = red16(ss); ss += __shfl_xor(ss, 16); rstd = rsqrtf(ss * (1.f / 128.f) + 1e-6f); g4 = *((const f32x4*)gn + (lane & 31)); }
.LBB0_26:
	s_andn2_b64 vcc, exec, s[16:17]
	s_cbranch_vccnz .LBB0_31
	v_readlane_b32 s3, v252, 6
	v_readlane_b32 s4, v255, 30
	s_add_i32 s16, s4, s3
	s_cmp_gt_i32 s16, 0x11fff
	s_cbranch_scc1 .LBB0_31
	s_load_dwordx2 s[44:45], s[90:91], 0x158
	s_load_dwordx2 s[46:47], s[90:91], 0x98
	v_lshlrev_b32_e32 v1, 3, v166
	v_lshlrev_b32_e32 v0, 4, v166
	v_mov_b32_e32 v2, 0x3b800000
	s_waitcnt lgkmcnt(0)
	global_load_dwordx4 v[4:7], v0, s[46:47]
	s_add_u32 s40, s44, 0x1b100000
	s_addc_u32 s41, s45, 0
	s_add_u32 s40, s40, 0x1000
	s_addc_u32 s41, s41, 0
	s_add_u32 s42, s44, 0x12100000
	s_addc_u32 s43, s45, 0
	s_add_u32 s48, s44, 0x9100000
	s_addc_u32 s49, s45, 0
.Lpd0_row:
	s_lshl_b32 s25, s16, 13
	s_add_u32 s4, s40, s25
	s_addc_u32 s5, s41, 0
	s_lshl_b32 s25, s16, 11
	s_add_u32 s6, s42, s25
	s_addc_u32 s7, s43, 0
	s_add_u32 s52, s48, s25
	s_addc_u32 s53, s49, 0
	global_load_dwordx2 v[8:9], v1, s[4:5] offset:0 nt
	global_load_dwordx2 v[10:11], v1, s[4:5] offset:512 nt
	global_load_dwordx2 v[12:13], v1, s[4:5] offset:1024 nt
	global_load_dwordx2 v[14:15], v1, s[4:5] offset:1536 nt
	global_load_dwordx2 v[16:17], v1, s[4:5] offset:2048 nt
	global_load_dwordx2 v[18:19], v1, s[4:5] offset:2560 nt
	global_load_dwordx2 v[20:21], v1, s[4:5] offset:3072 nt
	global_load_dwordx2 v[22:23], v1, s[4:5] offset:3584 nt
	global_load_dwordx2 v[24:25], v1, s[6:7] offset:0 nt
	global_load_dwordx2 v[26:27], v1, s[6:7] offset:512 nt
	global_load_dwordx2 v[28:29], v1, s[6:7] offset:1024 nt
	global_load_dwordx2 v[30:31], v1, s[6:7] offset:1536 nt
	s_waitcnt vmcnt(4)
	v_lshlrev_b32_e32 v32, 16, v8
	v_and_b32_e32 v33, 0xffff0000, v8
	v_lshlrev_b32_e32 v34, 16, v9
	v_and_b32_e32 v35, 0xffff0000, v9
	v_lshlrev_b32_e32 v52, 16, v16
	v_and_b32_e32 v53, 0xffff0000, v16
	v_lshlrev_b32_e32 v54, 16, v17
	v_and_b32_e32 v55, 0xffff0000, v17
	v_add_f32_e32 v32, v32, v52
	v_add_f32_e32 v33, v33, v53
	v_add_f32_e32 v34, v34, v54
	v_add_f32_e32 v35, v35, v55
	v_lshlrev_b32_e32 v36, 16, v10
	v_and_b32_e32 v37, 0xffff0000, v10
	v_lshlrev_b32_e32 v38, 16, v11
	v_and_b32_e32 v39, 0xffff0000, v11
	v_lshlrev_b32_e32 v56, 16, v18
	v_and_b32_e32 v57, 0xffff0000, v18
	v_lshlrev_b32_e32 v58, 16, v19
	v_and_b32_e32 v59, 0xffff0000, v19
	v_add_f32_e32 v36, v36, v56
	v_add_f32_e32 v37, v37, v57
	v_add_f32_e32 v38, v38, v58
	v_add_f32_e32 v39, v39, v59
	v_lshlrev_b32_e32 v40, 16, v12
	v_and_b32_e32 v41, 0xffff0000, v12
	v_lshlrev_b32_e32 v42, 16, v13
	v_and_b32_e32 v43, 0xffff0000, v13
	v_lshlrev_b32_e32 v60, 16, v20
	v_and_b32_e32 v61, 0xffff0000, v20
	v_lshlrev_b32_e32 v62, 16, v21
	v_and_b32_e32 v63, 0xffff0000, v21
	v_add_f32_e32 v40, v40, v60
	v_add_f32_e32 v41, v41, v61
	v_add_f32_e32 v42, v42, v62
	v_add_f32_e32 v43, v43, v63
	v_lshlrev_b32_e32 v44, 16, v14
	v_and_b32_e32 v45, 0xffff0000, v14
	v_lshlrev_b32_e32 v46, 16, v15
	v_and_b32_e32 v47, 0xffff0000, v15
	v_lshlrev_b32_e32 v64, 16, v22
	v_and_b32_e32 v65, 0xffff0000, v22
	v_lshlrev_b32_e32 v66, 16, v23
	v_and_b32_e32 v67, 0xffff0000, v23
	v_add_f32_e32 v44, v44, v64
	v_add_f32_e32 v45, v45, v65
	v_add_f32_e32 v46, v46, v66
	v_add_f32_e32 v47, v47, v67
	v_mul_f32_e32 v48, v32, v32
	v_mul_f32_e32 v49, v36, v36
	v_mul_f32_e32 v50, v40, v40
	v_mul_f32_e32 v51, v44, v44
	v_fmac_f32_e32 v48, v33, v33
	v_fmac_f32_e32 v49, v37, v37
	v_fmac_f32_e32 v50, v41, v41
	v_fmac_f32_e32 v51, v45, v45
	v_fmac_f32_e32 v48, v34, v34
	v_fmac_f32_e32 v49, v38, v38
	v_fmac_f32_e32 v50, v42, v42
	v_fmac_f32_e32 v51, v46, v46
	v_fmac_f32_e32 v48, v35, v35
	v_fmac_f32_e32 v49, v39, v39
	v_fmac_f32_e32 v50, v43, v43
	v_fmac_f32_e32 v51, v47, v47
	v_add_f32_dpp v48, v48, v48 quad_perm:[1,0,3,2] row_mask:0xf bank_mask:0xf bound_ctrl:1
	v_add_f32_dpp v49, v49, v49 quad_perm:[1,0,3,2] row_mask:0xf bank_mask:0xf bound_ctrl:1
	v_add_f32_dpp v50, v50, v50 quad_perm:[1,0,3,2] row_mask:0xf bank_mask:0xf bound_ctrl:1
	v_add_f32_dpp v51, v51, v51 quad_perm:[1,0,3,2] row_mask:0xf bank_mask:0xf bound_ctrl:1
	v_add_f32_dpp v48, v48, v48 quad_perm:[2,3,0,1] row_mask:0xf bank_mask:0xf bound_ctrl:1
	v_add_f32_dpp v49, v49, v49 quad_perm:[2,3,0,1] row_mask:0xf bank_mask:0xf bound_ctrl:1
	v_add_f32_dpp v50, v50, v50 quad_perm:[2,3,0,1] row_mask:0xf bank_mask:0xf bound_ctrl:1
	v_add_f32_dpp v51, v51, v51 quad_perm:[2,3,0,1] row_mask:0xf bank_mask:0xf bound_ctrl:1
	v_add_f32_dpp v48, v48, v48 row_half_mirror row_mask:0xf bank_mask:0xf bound_ctrl:1
	v_add_f32_dpp v49, v49, v49 row_half_mirror row_mask:0xf bank_mask:0xf bound_ctrl:1
	v_add_f32_dpp v50, v50, v50 row_half_mirror row_mask:0xf bank_mask:0xf bound_ctrl:1
	v_add_f32_dpp v51, v51, v51 row_half_mirror row_mask:0xf bank_mask:0xf bound_ctrl:1
	v_add_f32_dpp v48, v48, v48 row_mirror row_mask:0xf bank_mask:0xf bound_ctrl:1
	v_add_f32_dpp v49, v49, v49 row_mirror row_mask:0xf bank_mask:0xf bound_ctrl:1
	v_add_f32_dpp v50, v50, v50 row_mirror row_mask:0xf bank_mask:0xf bound_ctrl:1
	v_add_f32_dpp v51, v51, v51 row_mirror row_mask:0xf bank_mask:0xf bound_ctrl:1
	s_nop 0
	v_readlane_b32 s3, v48, 0
	v_readlane_b32 s8, v48, 16
	v_readlane_b32 s12, v48, 32
	v_readlane_b32 s21, v48, 48
	v_readlane_b32 s23, v49, 0
	v_readlane_b32 s25, v49, 16
	v_readlane_b32 s30, v49, 32
	v_readlane_b32 s32, v49, 48
	s_nop 1
	v_mov_b32_e32 v48, s3
	v_mov_b32_e32 v49, s23
	v_add_f32_e32 v48, s8, v48
	v_add_f32_e32 v49, s25, v49
	v_add_f32_e32 v48, s12, v48
	v_add_f32_e32 v49, s30, v49
	v_add_f32_e32 v48, s21, v48
	v_add_f32_e32 v49, s32, v49
	s_nop 0
	v_readlane_b32 s3, v50, 0
	v_readlane_b32 s8, v50, 16
	v_readlane_b32 s12, v50, 32
	v_readlane_b32 s21, v50, 48
	v_readlane_b32 s23, v51, 0
	v_readlane_b32 s25, v51, 16
	v_readlane_b32 s30, v51, 32
	v_readlane_b32 s32, v51, 48
	s_nop 1
	v_mov_b32_e32 v50, s3
	v_mov_b32_e32 v51, s23
	v_add_f32_e32 v50, s8, v50
	v_add_f32_e32 v51, s25, v51
	v_add_f32_e32 v50, s12, v50
	v_add_f32_e32 v51, s30, v51
	v_add_f32_e32 v50, s21, v50
	v_add_f32_e32 v51, s32, v51
	v_fmaak_f32 v48, v2, v48, 0x358637bd
	v_fmaak_f32 v49, v2, v49, 0x358637bd
	v_fmaak_f32 v50, v2, v50, 0x358637bd
	v_fmaak_f32 v51, v2, v51, 0x358637bd
	v_rsq_f32_e32 v48, v48
	v_rsq_f32_e32 v49, v49
	v_rsq_f32_e32 v50, v50
	v_rsq_f32_e32 v51, v51
	s_waitcnt vmcnt(0)
; DI float red16(float v) { v += DPPF(v, 0xB1); v += DPPF(v, 0x4E); v += DPPF(v, 0x141); v += DPPF(v, 0x140); return v; }
; DI f32x4 bf4_to_f4(u32x2 w) { return (f32x4){__uint_as_float(w.x << 16), __uint_as_float(w.x & 0xffff0000u), __uint_as_float(w.y << 16), __uint_as_float(w.y & 0xffff0000u)}; }
; DI u32x2 f4_to_bf4(f32x4 v) { return (u32x2){pk2(v.x, v.y), pk2(v.z, v.w)}; }
; template <int KIND> DI void post_diag_phase(const PZ& p, int wave, int lane) {
;     ...
;             if (KIND == 0) { rstd = rsqrtf(wave_sum(ss) * (1.f / 256.f) + 1e-6f); g4 = *((const f32x4*)gn + lane); }
;             else { ss = red16(ss); ss += __shfl_xor(ss, 16); rstd = rsqrtf(ss * (1.f / 128.f) + 1e-6f); g4 = *((const f32x4*)gn + (lane & 31)); }
;             const f32x4 og = bf4_to_f4(__builtin_nontemporal_load((const u32x2*)(OG + (size_t)m * 1024) + lane + 64 * j));
;             *((u32x2*)(HA + (size_t)m * 1024) + lane + 64 * j) = f4_to_bf4(o * rstd * g4 * og);
;         }
;     }
	v_lshlrev_b32_e32 v52, 16, v24
	v_and_b32_e32 v53, 0xffff0000, v24
	v_lshlrev_b32_e32 v54, 16, v25
	v_and_b32_e32 v55, 0xffff0000, v25
	v_lshlrev_b32_e32 v56, 16, v26
	v_and_b32_e32 v57, 0xffff0000, v26
	v_lshlrev_b32_e32 v58, 16, v27
	v_and_b32_e32 v59, 0xffff0000, v27
	v_lshlrev_b32_e32 v60, 16, v28
	v_and_b32_e32 v61, 0xffff0000, v28
	v_lshlrev_b32_e32 v62, 16, v29
	v_and_b32_e32 v63, 0xffff0000, v29
	v_lshlrev_b32_e32 v64, 16, v30
	v_and_b32_e32 v65, 0xffff0000, v30
	v_lshlrev_b32_e32 v66, 16, v31
	v_and_b32_e32 v67, 0xffff0000, v31
	v_mul_f32_e32 v32, v32, v48
	v_mul_f32_e32 v36, v36, v49
	v_mul_f32_e32 v40, v40, v50
	v_mul_f32_e32 v44, v44, v51
	v_mul_f32_e32 v33, v33, v48
	v_mul_f32_e32 v37, v37, v49
	v_mul_f32_e32 v41, v41, v50
	v_mul_f32_e32 v45, v45, v51
	v_mul_f32_e32 v34, v34, v48
	v_mul_f32_e32 v38, v38, v49
	v_mul_f32_e32 v42, v42, v50
	v_mul_f32_e32 v46, v46, v51
	v_mul_f32_e32 v35, v35, v48
	v_mul_f32_e32 v39, v39, v49
	v_mul_f32_e32 v43, v43, v50
	v_mul_f32_e32 v47, v47, v51
	v_mul_f32_e32 v32, v32, v4
	v_mul_f32_e32 v36, v36, v4
	v_mul_f32_e32 v40, v40, v4
	v_mul_f32_e32 v44, v44, v4
	v_mul_f32_e32 v33, v33, v5
	v_mul_f32_e32 v37, v37, v5
	v_mul_f32_e32 v41, v41, v5
	v_mul_f32_e32 v45, v45, v5
	v_mul_f32_e32 v34, v34, v6
	v_mul_f32_e32 v38, v38, v6
	v_mul_f32_e32 v42, v42, v6
	v_mul_f32_e32 v46, v46, v6
	v_mul_f32_e32 v35, v35, v7
	v_mul_f32_e32 v39, v39, v7
	v_mul_f32_e32 v43, v43, v7
	v_mul_f32_e32 v47, v47, v7
	v_mul_f32_e32 v32, v32, v52
	v_mul_f32_e32 v36, v36, v56
	v_mul_f32_e32 v40, v40, v60
	v_mul_f32_e32 v44, v44, v64
	v_mul_f32_e32 v33, v33, v53
	v_mul_f32_e32 v37, v37, v57
	v_mul_f32_e32 v41, v41, v61
	v_mul_f32_e32 v45, v45, v65
	v_mul_f32_e32 v34, v34, v54
	v_mul_f32_e32 v38, v38, v58
	v_mul_f32_e32 v42, v42, v62
	v_mul_f32_e32 v46, v46, v66
	v_mul_f32_e32 v35, v35, v55
	v_mul_f32_e32 v39, v39, v59
	v_mul_f32_e32 v43, v43, v63
	v_mul_f32_e32 v47, v47, v67
	v_cvt_pk_bf16_f32 v8, v32, v33
	v_cvt_pk_bf16_f32 v9, v34, v35
	v_cvt_pk_bf16_f32 v10, v36, v37
	v_cvt_pk_bf16_f32 v11, v38, v39
	v_cvt_pk_bf16_f32 v12, v40, v41
	v_cvt_pk_bf16_f32 v13, v42, v43
	v_cvt_pk_bf16_f32 v14, v44, v45
	v_cvt_pk_bf16_f32 v15, v46, v47
	global_store_dwordx2 v1, v[8:9], s[52:53] offset:0
	global_store_dwordx2 v1, v[10:11], s[52:53] offset:512
	global_store_dwordx2 v1, v[12:13], s[52:53] offset:1024
	global_store_dwordx2 v1, v[14:15], s[52:53] offset:1536
.Lpd0_next:
	s_add_i32 s16, s16, s92
	s_cmp_gt_i32 s16, 0x11fff
	s_cbranch_scc0 .Lpd0_row
	s_mov_b32 s93, 0x12100000

; DI f32x4 bf4_to_f4(u32x2 w) { return (f32x4){__uint_as_float(w.x << 16), __uint_as_float(w.x & 0xffff0000u), __uint_as_float(w.y << 16), __uint_as_float(w.y & 0xffff0000u)}; }
; DI u32x2 f4_to_bf4(f32x4 v) { return (u32x2){pk2(v.x, v.y), pk2(v.z, v.w)}; }
; DI void dx_phase(const PZ& p, int wave, int lane) {
;     const int gw = blockIdx.x * 8 + wave, NGW = gridDim.x * 8;
;     const bf16_t* HT = (const bf16_t*)(p.ws() + WS_BIG);
;     bf16_t* HA = (bf16_t*)(p.ws() + WS_HA);
;     for (int m = gw; m < MTOK; m += NGW) {
;         const int t = m % TT; const bool first = (t == 0 || t == NCTX), last = (t == NCTX - 1 || t == TT - 1);
;         const u32x2* hp = (const u32x2*)(HT + (size_t)m * 1024) + lane;
; #pragma unroll
;         for (int j = 0; j < 4; ++j) {
;             const u32x2 hraw = hp[64 * j];
;             const f32x4 h = bf4_to_f4(hraw);
;             f32x4 pv = (f32x4){0.f, 0.f, 0.f, 0.f}, nv = pv;
;             if (!first) pv = bf4_to_f4((hp - 256)[64 * j]);
;             if (!last) nv = bf4_to_f4((hp + 256)[64 * j]);
;             const f32x4 dx = (pv + nv) * 0.5f - h;
;             *((u32x2*)(HA + (size_t)m * 2048) + lane + 64 * j) = hraw;
;             *((u32x2*)(HA + (size_t)m * 2048 + 1024) + lane + 64 * j) = f4_to_bf4(dx);
;         }
;     }
.LBB0_1271:
	s_andn2_b64 vcc, exec, s[16:17]
	s_cbranch_vccnz .LBB0_1291
	v_readlane_b32 s2, v252, 6
	v_readlane_b32 s3, v255, 30
	s_add_i32 s16, s3, s2
	s_cmp_gt_i32 s16, 0x11fff
	s_cbranch_scc1 .LBB0_1291
	s_load_dwordx2 s[44:45], s[90:91], 0x158
	v_lshlrev_b32_e32 v1, 3, v166
	s_waitcnt lgkmcnt(0)
	s_add_u32 s40, s44, 0x1b100000
	s_addc_u32 s41, s45, 0
	s_add_u32 s42, s44, 0x9100000
	s_addc_u32 s43, s45, 0
	s_branch .Ldx_row
.Ldx_next:
	s_add_i32 s16, s16, s92
	s_cmp_gt_i32 s16, 0x11fff
	s_cbranch_scc1 .LBB0_1291
.Ldx_row:
	s_mul_hi_i32 s21, s16, 0x38e38e39
	s_lshr_b32 s23, s21, 31
	s_ashr_i32 s21, s21, 9
	s_add_i32 s21, s21, s23
	s_mul_i32 s23, s21, 0xfffff700
	s_add_i32 s23, s23, s16
	s_lshl_b32 s25, s16, 11
	s_add_u32 s2, s40, s25
	s_addc_u32 s3, s41, 0
	s_lshl_b32 s25, s16, 12
	s_add_u32 s4, s42, s25
	s_addc_u32 s5, s43, 0
	global_load_dwordx2 v[4:5], v1, s[2:3] offset:0
	global_load_dwordx2 v[6:7], v1, s[2:3] offset:512
	global_load_dwordx2 v[8:9], v1, s[2:3] offset:1024
	global_load_dwordx2 v[10:11], v1, s[2:3] offset:1536
	s_cmp_eq_u32 s23, 0
	s_cbranch_scc1 .Ldx_noprev
	s_cmpk_eq_i32 s23, 0x100
	s_cbranch_scc1 .Ldx_noprev
	s_sub_u32 s6, s2, 0x800
	s_subb_u32 s7, s3, 0
	global_load_dwordx2 v[12:13], v1, s[6:7] offset:0
	global_load_dwordx2 v[14:15], v1, s[6:7] offset:512
	global_load_dwordx2 v[16:17], v1, s[6:7] offset:1024
	global_load_dwordx2 v[18:19], v1, s[6:7] offset:1536
	s_branch .Ldx_prevdone
.Ldx_noprev:
	v_mov_b32_e32 v12, 0
	v_mov_b32_e32 v13, 0
	v_mov_b32_e32 v14, 0
	v_mov_b32_e32 v15, 0
	v_mov_b32_e32 v16, 0
	v_mov_b32_e32 v17, 0
	v_mov_b32_e32 v18, 0
	v_mov_b32_e32 v19, 0
.Ldx_prevdone:
	s_cmpk_eq_i32 s23, 0xff
	s_cbranch_scc1 .Ldx_nonext
	s_cmpk_eq_i32 s23, 0x8ff
	s_cbranch_scc1 .Ldx_nonext
	s_add_u32 s6, s2, 0x800
	s_addc_u32 s7, s3, 0
	global_load_dwordx2 v[20:21], v1, s[6:7] offset:0
	global_load_dwordx2 v[22:23], v1, s[6:7] offset:512
	global_load_dwordx2 v[24:25], v1, s[6:7] offset:1024
	global_load_dwordx2 v[26:27], v1, s[6:7] offset:1536
	s_branch .Ldx_nextdone
.Ldx_nonext:
	v_mov_b32_e32 v20, 0
	v_mov_b32_e32 v21, 0
	v_mov_b32_e32 v22, 0
	v_mov_b32_e32 v23, 0
	v_mov_b32_e32 v24, 0
	v_mov_b32_e32 v25, 0
	v_mov_b32_e32 v26, 0
	v_mov_b32_e32 v27, 0
.Ldx_nextdone:
	s_waitcnt vmcnt(0)
	v_lshlrev_b32_e32 v36, 16, v12
	v_lshlrev_b32_e32 v37, 16, v20
	v_lshlrev_b32_e32 v38, 16, v4
	v_and_b32_e32 v39, 0xffff0000, v12
	v_and_b32_e32 v40, 0xffff0000, v20
	v_and_b32_e32 v41, 0xffff0000, v4
	v_add_f32_e32 v36, v36, v37
	v_add_f32_e32 v39, v39, v40
	v_fma_f32 v36, v36, 0.5, -v38
	v_fma_f32 v39, v39, 0.5, -v41
	v_cvt_pk_bf16_f32 v28, v36, v39
	v_lshlrev_b32_e32 v36, 16, v13
	v_lshlrev_b32_e32 v37, 16, v21
	v_lshlrev_b32_e32 v38, 16, v5
	v_and_b32_e32 v39, 0xffff0000, v13
	v_and_b32_e32 v40, 0xffff0000, v21
	v_and_b32_e32 v41, 0xffff0000, v5
	v_add_f32_e32 v36, v36, v37
	v_add_f32_e32 v39, v39, v40
	v_fma_f32 v36, v36, 0.5, -v38
	v_fma_f32 v39, v39, 0.5, -v41
	v_cvt_pk_bf16_f32 v29, v36, v39
	v_lshlrev_b32_e32 v36, 16, v14
	v_lshlrev_b32_e32 v37, 16, v22
	v_lshlrev_b32_e32 v38, 16, v6
	v_and_b32_e32 v39, 0xffff0000, v14
	v_and_b32_e32 v40, 0xffff0000, v22
	v_and_b32_e32 v41, 0xffff0000, v6
	v_add_f32_e32 v36, v36, v37
	v_add_f32_e32 v39, v39, v40
	v_fma_f32 v36, v36, 0.5, -v38
	v_fma_f32 v39, v39, 0.5, -v41
	v_cvt_pk_bf16_f32 v30, v36, v39
	v_lshlrev_b32_e32 v36, 16, v15
	v_lshlrev_b32_e32 v37, 16, v23
	v_lshlrev_b32_e32 v38, 16, v7
	v_and_b32_e32 v39, 0xffff0000, v15
	v_and_b32_e32 v40, 0xffff0000, v23
	v_and_b32_e32 v41, 0xffff0000, v7
	v_add_f32_e32 v36, v36, v37
	v_add_f32_e32 v39, v39, v40
	v_fma_f32 v36, v36, 0.5, -v38
	v_fma_f32 v39, v39, 0.5, -v41
	v_cvt_pk_bf16_f32 v31, v36, v39
	v_lshlrev_b32_e32 v36, 16, v16
	v_lshlrev_b32_e32 v37, 16, v24
	v_lshlrev_b32_e32 v38, 16, v8
	v_and_b32_e32 v39, 0xffff0000, v16
	v_and_b32_e32 v40, 0xffff0000, v24
	v_and_b32_e32 v41, 0xffff0000, v8
	v_add_f32_e32 v36, v36, v37
	v_add_f32_e32 v39, v39, v40
	v_fma_f32 v36, v36, 0.5, -v38
	v_fma_f32 v39, v39, 0.5, -v41
	v_cvt_pk_bf16_f32 v32, v36, v39
	v_lshlrev_b32_e32 v36, 16, v17
	v_lshlrev_b32_e32 v37, 16, v25
	v_lshlrev_b32_e32 v38, 16, v9
	v_and_b32_e32 v39, 0xffff0000, v17
	v_and_b32_e32 v40, 0xffff0000, v25
	v_and_b32_e32 v41, 0xffff0000, v9
	v_add_f32_e32 v36, v36, v37
	v_add_f32_e32 v39, v39, v40
	v_fma_f32 v36, v36, 0.5, -v38
	v_fma_f32 v39, v39, 0.5, -v41
	v_cvt_pk_bf16_f32 v33, v36, v39
	v_lshlrev_b32_e32 v36, 16, v18
	v_lshlrev_b32_e32 v37, 16, v26
	v_lshlrev_b32_e32 v38, 16, v10
	v_and_b32_e32 v39, 0xffff0000, v18
	v_and_b32_e32 v40, 0xffff0000, v26
	v_and_b32_e32 v41, 0xffff0000, v10
	v_add_f32_e32 v36, v36, v37
	v_add_f32_e32 v39, v39, v40
	v_fma_f32 v36, v36, 0.5, -v38
	v_fma_f32 v39, v39, 0.5, -v41
	v_cvt_pk_bf16_f32 v34, v36, v39
	v_lshlrev_b32_e32 v36, 16, v19
	v_lshlrev_b32_e32 v37, 16, v27
	v_lshlrev_b32_e32 v38, 16, v11
	v_and_b32_e32 v39, 0xffff0000, v19
	v_and_b32_e32 v40, 0xffff0000, v27
	v_and_b32_e32 v41, 0xffff0000, v11
	v_add_f32_e32 v36, v36, v37
	v_add_f32_e32 v39, v39, v40
	v_fma_f32 v36, v36, 0.5, -v38
	v_fma_f32 v39, v39, 0.5, -v41
	v_cvt_pk_bf16_f32 v35, v36, v39
	global_store_dwordx2 v1, v[4:5], s[4:5] offset:0
	global_store_dwordx2 v1, v[6:7], s[4:5] offset:512
	global_store_dwordx2 v1, v[8:9], s[4:5] offset:1024
	global_store_dwordx2 v1, v[10:11], s[4:5] offset:1536
	global_store_dwordx2 v1, v[28:29], s[4:5] offset:2048
	global_store_dwordx2 v1, v[30:31], s[4:5] offset:2560
	global_store_dwordx2 v1, v[32:33], s[4:5] offset:3072
	global_store_dwordx2 v1, v[34:35], s[4:5] offset:3584
	s_branch .Ldx_next

; __device__ __forceinline__ void xcd_barrier(const XcdBarrier& b) {
;     asm volatile("s_waitcnt vmcnt(0)" ::: "memory");
;     __syncthreads();
;     if (threadIdx.x == 0) {
;         unsigned* bar = b.bar;
;         __builtin_amdgcn_s_waitcnt(0);
;         unsigned nloc = b.st[0], nx = b.st[1];
;         if (nloc == 0u) { xcd_barrier_complete(bar, b.x, nloc, nx); b.st[0] = nloc; b.st[1] = nx; }
; __global__ void __launch_bounds__(512, 2) mega_fwd(P kp) {
;     ...
;         if (ph + 1 < kp.ph_hi) {
;             if (!sync_after) __syncthreads();
;             else if (nsync++ == 0) grid.sync();
;             else xcd_barrier(xbar);
;         }
.LBB0_1747:
	s_cmp_lg_u32 s12, 0
	s_waitcnt vmcnt(0)
	s_barrier
	s_mov_b64 s[16:17], exec
	v_readlane_b32 s4, v252, 2
	v_readlane_b32 s5, v252, 3
	s_and_b64 s[4:5], s[16:17], s[4:5]
	s_mov_b64 exec, s[4:5]
	s_cbranch_execz .LBB0_1807
	v_readlane_b32 s4, v254, 48
	s_waitcnt vmcnt(0) expcnt(0) lgkmcnt(0)
	s_nop 0
	v_mov_b32_e32 v0, s4
	ds_read_b32 v2, v0
	v_readlane_b32 s4, v254, 49
	s_waitcnt lgkmcnt(0)
	v_cmp_ne_u32_e32 vcc, 0, v2
	v_mov_b32_e32 v0, s4
	ds_read_b32 v0, v0
	s_cbranch_vccnz .LBB0_1765
	s_mov_b32 s4, 1
	s_branch .LBB0_1752
